# DA: the 4 row-sum MFMAs issued by the softmax wave at the end of its block (MFMA block = 24 MFMAs + LDS reads only)
# baseline (speedup 1.0000x reference)
.LBB0_599:
	s_barrier
	s_setprio 3
	ds_read_b64_tr_b16 v[194:195], v238 offset:0
	ds_read_b64_tr_b16 v[196:197], v238 offset:0x800
	ds_read_b64_tr_b16 v[198:199], v238 offset:0x200
	ds_read_b64_tr_b16 v[200:201], v238 offset:0xa00
	ds_read_b64_tr_b16 v[202:203], v238 offset:0x400
	ds_read_b64_tr_b16 v[204:205], v238 offset:0xc00
	ds_read_b64_tr_b16 v[206:207], v238 offset:0x600
	ds_read_b64_tr_b16 v[208:209], v238 offset:0xe00
	ds_read_b128 v[226:229], v188 offset:45056
	ds_read_b128 v[230:233], v189 offset:40960
	ds_read_b128 v[234:237], v189 offset:45056
	s_waitcnt lgkmcnt(9)
	v_mfma_f32_32x32x16_bf16 v[50:65], v[142:145], v[194:197], v[50:65]
	ds_read_b64_tr_b16 v[210:211], v238 offset:0x1000
	ds_read_b64_tr_b16 v[212:213], v238 offset:0x1800
	s_waitcnt lgkmcnt(9)
	v_mfma_f32_32x32x16_bf16 v[34:49], v[142:145], v[198:201], v[34:49]
	ds_read_b64_tr_b16 v[214:215], v238 offset:0x1200
	ds_read_b64_tr_b16 v[216:217], v238 offset:0x1a00
	s_waitcnt lgkmcnt(9)
	v_mfma_f32_32x32x16_bf16 v[18:33], v[142:145], v[202:205], v[18:33]
	ds_read_b64_tr_b16 v[218:219], v238 offset:0x1400
	ds_read_b64_tr_b16 v[220:221], v238 offset:0x1c00
	s_waitcnt lgkmcnt(9)
	v_mfma_f32_32x32x16_bf16 v[2:17], v[142:145], v[206:209], v[2:17]
	ds_read_b64_tr_b16 v[222:223], v238 offset:0x1600
	ds_read_b64_tr_b16 v[224:225], v238 offset:0x1e00
	s_waitcnt lgkmcnt(6)
	v_mfma_f32_32x32x16_bf16 v[50:65], v[138:141], v[210:213], v[50:65]
	ds_read_b64_tr_b16 v[194:195], v238 offset:0x2000
	ds_read_b64_tr_b16 v[196:197], v238 offset:0x2800
	s_waitcnt lgkmcnt(6)
	v_mfma_f32_32x32x16_bf16 v[34:49], v[138:141], v[214:217], v[34:49]
	ds_read_b64_tr_b16 v[198:199], v238 offset:0x2200
	ds_read_b64_tr_b16 v[200:201], v238 offset:0x2a00
	s_waitcnt lgkmcnt(6)
	v_mfma_f32_32x32x16_bf16 v[18:33], v[138:141], v[218:221], v[18:33]
	ds_read_b64_tr_b16 v[202:203], v238 offset:0x2400
	ds_read_b64_tr_b16 v[204:205], v238 offset:0x2c00
	s_waitcnt lgkmcnt(6)
	v_mfma_f32_32x32x16_bf16 v[2:17], v[138:141], v[222:225], v[2:17]
	ds_read_b64_tr_b16 v[206:207], v238 offset:0x2600
	ds_read_b64_tr_b16 v[208:209], v238 offset:0x2e00
	s_waitcnt lgkmcnt(6)
	v_mfma_f32_32x32x16_bf16 v[50:65], v[134:137], v[194:197], v[50:65]
	ds_read_b64_tr_b16 v[210:211], v238 offset:0x3000
	ds_read_b64_tr_b16 v[212:213], v238 offset:0x3800
	s_waitcnt lgkmcnt(6)
	v_mfma_f32_32x32x16_bf16 v[34:49], v[134:137], v[198:201], v[34:49]
	ds_read_b64_tr_b16 v[214:215], v238 offset:0x3200
	ds_read_b64_tr_b16 v[216:217], v238 offset:0x3a00
	s_waitcnt lgkmcnt(6)
	v_mfma_f32_32x32x16_bf16 v[18:33], v[134:137], v[202:205], v[18:33]
	ds_read_b64_tr_b16 v[218:219], v238 offset:0x3400
	ds_read_b64_tr_b16 v[220:221], v238 offset:0x3c00
	s_waitcnt lgkmcnt(6)
	v_mfma_f32_32x32x16_bf16 v[2:17], v[134:137], v[206:209], v[2:17]
	ds_read_b64_tr_b16 v[222:223], v238 offset:0x3600
	ds_read_b64_tr_b16 v[224:225], v238 offset:0x3e00
	s_waitcnt lgkmcnt(6)
	v_mfma_f32_32x32x16_bf16 v[50:65], v[130:133], v[210:213], v[50:65]
	ds_read_b128 v[82:85], v188 offset:40960
	ds_read_b128 v[194:197], v190 offset:40960
	s_waitcnt lgkmcnt(6)
	v_mfma_f32_32x32x16_bf16 v[34:49], v[130:133], v[214:217], v[34:49]
	ds_read_b128 v[198:201], v190 offset:45056
	s_waitcnt lgkmcnt(5)
	v_mfma_f32_32x32x16_bf16 v[18:33], v[130:133], v[218:221], v[18:33]
	ds_read_b128 v[202:205], v191 offset:40960
	s_waitcnt lgkmcnt(4)
	v_mfma_f32_32x32x16_bf16 v[2:17], v[130:133], v[222:225], v[2:17]
	ds_read_b128 v[206:209], v191 offset:45056
	s_waitcnt lgkmcnt(4)
	v_mfma_f32_32x32x16_bf16 v[98:113], v[82:85], v[126:129], v[66:81]
	v_mfma_f32_32x32x16_bf16 v[82:97], v[226:229], v[126:129], v[66:81]
	v_mfma_f32_32x32x16_bf16 v[98:113], v[230:233], v[122:125], v[98:113]
	v_mfma_f32_32x32x16_bf16 v[82:97], v[234:237], v[122:125], v[82:97]
	s_waitcnt lgkmcnt(3)
	v_mfma_f32_32x32x16_bf16 v[98:113], v[194:197], v[118:121], v[98:113]
	s_waitcnt lgkmcnt(2)
	v_mfma_f32_32x32x16_bf16 v[82:97], v[198:201], v[118:121], v[82:97]
	s_waitcnt lgkmcnt(1)
	v_mfma_f32_32x32x16_bf16 v[98:113], v[202:205], v[114:117], v[98:113]
	s_waitcnt lgkmcnt(0)
	v_mfma_f32_32x32x16_bf16 v[82:97], v[206:209], v[114:117], v[82:97]

.LBB0_610:
	v_exp_f32_e32 v98, v98
	v_exp_f32_e32 v99, v99
	v_exp_f32_e32 v100, v100
	v_exp_f32_e32 v101, v101
	v_exp_f32_e32 v102, v102
	v_exp_f32_e32 v103, v103
	v_exp_f32_e32 v104, v104
	v_exp_f32_e32 v105, v105
	v_exp_f32_e32 v106, v106
	v_exp_f32_e32 v107, v107
	v_exp_f32_e32 v108, v108
	v_exp_f32_e32 v109, v109
	v_exp_f32_e32 v110, v110
	v_exp_f32_e32 v111, v111
	v_exp_f32_e32 v112, v112
	v_exp_f32_e32 v113, v113
	v_exp_f32_e32 v82, v82
	v_exp_f32_e32 v83, v83
	v_exp_f32_e32 v84, v84
	v_exp_f32_e32 v85, v85
	v_exp_f32_e32 v86, v86
	v_exp_f32_e32 v87, v87
	v_exp_f32_e32 v88, v88
	v_exp_f32_e32 v89, v89
	v_exp_f32_e32 v90, v90
	v_exp_f32_e32 v91, v91
	v_exp_f32_e32 v92, v92
	v_exp_f32_e32 v93, v93
	v_exp_f32_e32 v94, v94
	v_exp_f32_e32 v95, v95
	v_exp_f32_e32 v96, v96
	v_exp_f32_e32 v97, v97
	s_and_b64 vcc, exec, s[2:3]
	v_cvt_pk_bf16_f32 v142, v98, v99
	v_cvt_pk_bf16_f32 v143, v100, v101
	v_cvt_pk_bf16_f32 v144, v102, v103
	v_cvt_pk_bf16_f32 v145, v104, v105
	v_cvt_pk_bf16_f32 v138, v106, v107
	v_cvt_pk_bf16_f32 v139, v108, v109
	v_cvt_pk_bf16_f32 v140, v110, v111
	v_cvt_pk_bf16_f32 v141, v112, v113
	v_cvt_pk_bf16_f32 v134, v82, v83
	v_cvt_pk_bf16_f32 v135, v84, v85
	v_cvt_pk_bf16_f32 v136, v86, v87
	v_cvt_pk_bf16_f32 v137, v88, v89
	v_cvt_pk_bf16_f32 v130, v90, v91
	v_cvt_pk_bf16_f32 v131, v92, v93
	v_cvt_pk_bf16_f32 v132, v94, v95
	v_cvt_pk_bf16_f32 v133, v96, v97
	s_nop 1
	v_mfma_f32_16x16x32_bf16 v[244:247], v[142:145], v[248:251], v[244:247]
	v_mfma_f32_16x16x32_bf16 v[244:247], v[138:141], v[248:251], v[244:247]
	v_mfma_f32_16x16x32_bf16 v[244:247], v[134:137], v[248:251], v[244:247]
	v_mfma_f32_16x16x32_bf16 v[244:247], v[130:133], v[248:251], v[244:247]
	s_cbranch_vccnz .LBB0_612
	s_waitcnt vmcnt(1)
.LBB0_612:
	s_barrier
	s_setprio 3
	v_add_u32_e32 v197, s75, v193
	ds_read_b64_tr_b16 v[198:199], v197 offset:0
	ds_read_b64_tr_b16 v[200:201], v197 offset:0x800
	ds_read_b64_tr_b16 v[202:203], v197 offset:0x200
	ds_read_b64_tr_b16 v[204:205], v197 offset:0xa00
	ds_read_b64_tr_b16 v[206:207], v197 offset:0x400
	ds_read_b64_tr_b16 v[208:209], v197 offset:0xc00
	ds_read_b64_tr_b16 v[210:211], v197 offset:0x600
	ds_read_b64_tr_b16 v[212:213], v197 offset:0xe00
	ds_read_b128 v[230:233], v188 offset:36864
	ds_read_b128 v[234:237], v189 offset:32768
	ds_read_b128 v[238:241], v189 offset:36864
	s_waitcnt lgkmcnt(9)
	v_mfma_f32_32x32x16_bf16 v[50:65], v[142:145], v[198:201], v[50:65]
	ds_read_b64_tr_b16 v[214:215], v197 offset:0x1000
	ds_read_b64_tr_b16 v[216:217], v197 offset:0x1800
	s_waitcnt lgkmcnt(9)
	v_mfma_f32_32x32x16_bf16 v[34:49], v[142:145], v[202:205], v[34:49]
	ds_read_b64_tr_b16 v[218:219], v197 offset:0x1200
	ds_read_b64_tr_b16 v[220:221], v197 offset:0x1a00
	s_waitcnt lgkmcnt(9)
	v_mfma_f32_32x32x16_bf16 v[18:33], v[142:145], v[206:209], v[18:33]
	ds_read_b64_tr_b16 v[222:223], v197 offset:0x1400
	ds_read_b64_tr_b16 v[224:225], v197 offset:0x1c00
	s_waitcnt lgkmcnt(9)
	v_mfma_f32_32x32x16_bf16 v[2:17], v[142:145], v[210:213], v[2:17]
	ds_read_b64_tr_b16 v[226:227], v197 offset:0x1600
	ds_read_b64_tr_b16 v[228:229], v197 offset:0x1e00
	s_waitcnt lgkmcnt(6)
	v_mfma_f32_32x32x16_bf16 v[50:65], v[138:141], v[214:217], v[50:65]
	ds_read_b64_tr_b16 v[198:199], v197 offset:0x2000
	ds_read_b64_tr_b16 v[200:201], v197 offset:0x2800
	s_waitcnt lgkmcnt(6)
	v_mfma_f32_32x32x16_bf16 v[34:49], v[138:141], v[218:221], v[34:49]
	ds_read_b64_tr_b16 v[202:203], v197 offset:0x2200
	ds_read_b64_tr_b16 v[204:205], v197 offset:0x2a00
	s_waitcnt lgkmcnt(6)
	v_mfma_f32_32x32x16_bf16 v[18:33], v[138:141], v[222:225], v[18:33]
	ds_read_b64_tr_b16 v[206:207], v197 offset:0x2400
	ds_read_b64_tr_b16 v[208:209], v197 offset:0x2c00
	s_waitcnt lgkmcnt(6)
	v_mfma_f32_32x32x16_bf16 v[2:17], v[138:141], v[226:229], v[2:17]
	ds_read_b64_tr_b16 v[210:211], v197 offset:0x2600
	ds_read_b64_tr_b16 v[212:213], v197 offset:0x2e00
	s_waitcnt lgkmcnt(6)
	v_mfma_f32_32x32x16_bf16 v[50:65], v[134:137], v[198:201], v[50:65]
	ds_read_b64_tr_b16 v[214:215], v197 offset:0x3000
	ds_read_b64_tr_b16 v[216:217], v197 offset:0x3800
	s_waitcnt lgkmcnt(6)
	v_mfma_f32_32x32x16_bf16 v[34:49], v[134:137], v[202:205], v[34:49]
	ds_read_b64_tr_b16 v[218:219], v197 offset:0x3200
	ds_read_b64_tr_b16 v[220:221], v197 offset:0x3a00
	s_waitcnt lgkmcnt(6)
	v_mfma_f32_32x32x16_bf16 v[18:33], v[134:137], v[206:209], v[18:33]
	ds_read_b64_tr_b16 v[222:223], v197 offset:0x3400
	ds_read_b64_tr_b16 v[224:225], v197 offset:0x3c00
	s_waitcnt lgkmcnt(6)
	v_mfma_f32_32x32x16_bf16 v[2:17], v[134:137], v[210:213], v[2:17]
	ds_read_b64_tr_b16 v[226:227], v197 offset:0x3600
	ds_read_b64_tr_b16 v[228:229], v197 offset:0x3e00
	s_waitcnt lgkmcnt(6)
	v_mfma_f32_32x32x16_bf16 v[50:65], v[130:133], v[214:217], v[50:65]
	ds_read_b128 v[82:85], v188 offset:32768
	ds_read_b128 v[198:201], v190 offset:32768
	s_waitcnt lgkmcnt(6)
	v_mfma_f32_32x32x16_bf16 v[34:49], v[130:133], v[218:221], v[34:49]
	ds_read_b128 v[202:205], v190 offset:36864
	s_waitcnt lgkmcnt(5)
	v_mfma_f32_32x32x16_bf16 v[18:33], v[130:133], v[222:225], v[18:33]
	ds_read_b128 v[206:209], v191 offset:32768
	s_waitcnt lgkmcnt(4)
	v_mfma_f32_32x32x16_bf16 v[2:17], v[130:133], v[226:229], v[2:17]
	ds_read_b128 v[210:213], v191 offset:36864
	s_waitcnt lgkmcnt(4)
	v_mfma_f32_32x32x16_bf16 v[98:113], v[82:85], v[126:129], v[66:81]
	v_mfma_f32_32x32x16_bf16 v[82:97], v[230:233], v[126:129], v[66:81]
	v_mfma_f32_32x32x16_bf16 v[98:113], v[234:237], v[122:125], v[98:113]
	v_mfma_f32_32x32x16_bf16 v[82:97], v[238:241], v[122:125], v[82:97]
	s_waitcnt lgkmcnt(3)
	v_mfma_f32_32x32x16_bf16 v[98:113], v[198:201], v[118:121], v[98:113]
	s_waitcnt lgkmcnt(2)
	v_mfma_f32_32x32x16_bf16 v[82:97], v[202:205], v[118:121], v[82:97]
	s_waitcnt lgkmcnt(1)
	v_mfma_f32_32x32x16_bf16 v[98:113], v[206:209], v[114:117], v[98:113]
	s_waitcnt lgkmcnt(0)
	v_mfma_f32_32x32x16_bf16 v[82:97], v[210:213], v[114:117], v[82:97]
	s_and_b64 vcc, exec, s[6:7]
	s_cbranch_vccnz .LBB0_614
	s_waitcnt vmcnt(1)
